# phase 2: Z prefetch + mu in LDS + sigmoid reciprocal via v_rcp_f32 (on v30)
# speedup vs baseline: 1.0017x; 1.0017x over previous
.Lp2_epi:
	v_bfe_u32 v139, v142, 16, 1
	v_bfe_u32 v138, v143, 16, 1
	v_add3_u32 v139, v142, v139, s46
	v_add3_u32 v138, v143, v138, s46
	v_lshrrev_b32_e32 v139, 16, v139
	v_and_or_b32 v140, v138, s45, v139
	v_bfe_u32 v139, v144, 16, 1
	v_bfe_u32 v138, v145, 16, 1
	v_add3_u32 v139, v144, v139, s46
	v_add3_u32 v138, v145, v138, s46
	v_lshrrev_b32_e32 v139, 16, v139
	v_and_or_b32 v141, v138, s45, v139
	v_add_f32_e32 v139, v122, v146
	v_mul_f32_e32 v139, 0xbfb8aa3b, v139
	v_add_f32_e32 v138, v123, v147
	v_exp_f32_e32 v142, v139
	v_add_f32_e32 v139, v125, v149
	v_mul_f32_e32 v138, 0xbfb8aa3b, v138
	v_mul_f32_e32 v139, 0xbfb8aa3b, v139
	v_exp_f32_e32 v138, v138
	v_exp_f32_e32 v139, v139
	v_add_f32_e32 v143, v124, v148
	v_mul_f32_e32 v143, 0xbfb8aa3b, v143
	v_exp_f32_e32 v143, v143
	v_pk_add_f32 v[138:139], v[138:139], 1.0 op_sel_hi:[1,0]
	v_ashrrev_i32_e32 v187, 31, v186
	s_nop 0
	v_rcp_f32_e32 v169, v138
	v_pk_add_f32 v[148:149], v[192:193], v[194:195]
	v_rcp_f32_e32 v171, v139
	v_pk_add_f32 v[138:139], v[142:143], 1.0 op_sel_hi:[1,0]
	s_nop 0
	s_nop 0
	v_rcp_f32_e32 v173, v139
	v_pk_add_f32 v[146:147], v[188:189], v[190:191]
	v_rcp_f32_e32 v175, v138
	v_bfe_u32 v138, v131, 16, 1
	v_add3_u32 v131, v131, v138, s46
	v_bfe_u32 v138, v130, 16, 1
	v_add3_u32 v130, v130, v138, s46
	v_lshrrev_b32_e32 v130, 16, v130
	v_and_or_b32 v138, v131, s45, v130
	v_bfe_u32 v131, v132, 16, 1
	v_bfe_u32 v130, v133, 16, 1
	v_add3_u32 v131, v132, v131, s46
	v_add3_u32 v130, v133, v130, s46
	v_lshrrev_b32_e32 v131, 16, v131
	v_and_or_b32 v139, v130, s45, v131
	v_add_f32_e32 v131, v126, v134
	v_mul_f32_e32 v131, 0xbfb8aa3b, v131
	v_add_f32_e32 v130, v127, v135
	v_exp_f32_e32 v132, v131
	v_add_f32_e32 v131, v129, v137
	v_mul_f32_e32 v130, 0xbfb8aa3b, v130
	v_mul_f32_e32 v131, 0xbfb8aa3b, v131
	v_exp_f32_e32 v130, v130
	v_exp_f32_e32 v131, v131
	v_add_f32_e32 v133, v128, v136
	v_mul_f32_e32 v133, 0xbfb8aa3b, v133
	v_exp_f32_e32 v133, v133
	v_pk_add_f32 v[130:131], v[130:131], 1.0 op_sel_hi:[1,0]
	v_pk_add_f32 v[142:143], v[196:197], v[198:199]
	v_pk_add_f32 v[144:145], v[200:201], v[202:203]
	v_rcp_f32_e32 v134, v130
	s_nop 0
	v_rcp_f32_e32 v135, v131
	v_pk_add_f32 v[130:131], v[132:133], 1.0 op_sel_hi:[1,0]
	s_nop 0
	s_nop 0
	v_rcp_f32_e32 v132, v131
	s_nop 0
	v_rcp_f32_e32 v133, v130
	v_lshlrev_b64 v[130:131], 13, v[186:187]
	v_lshl_add_u64 v[130:131], v[180:181], 0, v[130:131]
	v_bfe_u32 v136, v135, 16, 1
	v_bfe_u32 v137, v134, 16, 1
	global_store_dwordx4 v[130:131], v[146:149], off
	global_store_dwordx4 v[130:131], v[142:145], off offset:16
	v_add3_u32 v134, v134, v137, s46
	v_add3_u32 v135, v135, v136, s46
	v_bfe_u32 v136, v133, 16, 1
	v_bfe_u32 v137, v132, 16, 1
	v_bfe_u32 v142, v175, 16, 1
	v_bfe_u32 v143, v173, 16, 1
	v_bfe_u32 v130, v171, 16, 1
	v_bfe_u32 v131, v169, 16, 1
	v_add3_u32 v143, v173, v143, s46
	v_add3_u32 v142, v175, v142, s46
	v_add3_u32 v132, v132, v137, s46
	v_add3_u32 v133, v133, v136, s46
	v_add3_u32 v131, v169, v131, s46
	v_add3_u32 v130, v171, v130, s46
	v_lshrrev_b32_e32 v136, 16, v133
	v_lshrrev_b32_e32 v137, 16, v132
	v_lshrrev_b32_e32 v132, 16, v142
	v_lshrrev_b32_e32 v133, 16, v143
	v_and_or_b32 v133, v130, s45, v133
	v_and_or_b32 v132, v131, s45, v132
	v_and_or_b32 v131, v135, s45, v137
	v_and_or_b32 v130, v134, s45, v136
	v_lshlrev_b64 v[134:135], 12, v[186:187]
	v_lshl_add_u64 v[136:137], v[182:183], 0, v[134:135]
	global_store_dwordx4 v[136:137], v[130:133], off
	s_nop 1
	s_nop 1
	v_lshl_add_u64 v[130:131], v[184:185], 0, v[134:135]
	global_store_dwordx4 v[130:131], v[138:141], off
	s_branch .LBB0_302
